# combo_dppspread
# baseline (speedup 1.0000x reference)
; __device__ __forceinline__ void phase_scan(const Params& p, int bid, int nblk, int wv) {
;     ...
;           for (int jj = 0; jj < 8; ++jj) {
;             const int s = sb * 8 + jj;
;             const int sn = (s + 1) & 31;
;             const float* qn = q + sn * 64;
;             f32x2 sa0 = S0[0] * kkn0.lo, sa1 = S1[0] * kkn0.lo, yp0 = S0[0] * wr0.lo, yp1 = S1[0] * wr0.lo;
;             sa0 += S0[1] * kkn0.hi; sa1 += S1[1] * kkn0.hi; yp0 += S0[1] * wr0.hi; yp1 += S1[1] * wr0.hi;
;             sa0 += S0[2] * kkn1.lo; sa1 += S1[2] * kkn1.lo; yp0 += S0[2] * wr1.lo; yp1 += S1[2] * wr1.lo;
;             sa0 += S0[3] * kkn1.hi; sa1 += S1[3] * kkn1.hi; yp0 += S0[3] * wr1.hi; yp1 += S1[3] * wr1.hi;
;             kkn0 = *reinterpret_cast<const f32x4*>(qn); kkn1 = *reinterpret_cast<const f32x4*>(qn + 4);
;             wr0 = *reinterpret_cast<const f32x4*>(qn + 2048); wr1 = *reinterpret_cast<const f32x4*>(qn + 2048 + 4);
;             float a0 = reduce8_np(sa0.x + sa0.y), p0 = reduce8_np(yp0.x + yp0.y);
;             float a1 = reduce8_np(sa1.x + sa1.y), p1 = reduce8_np(yp1.x + yp1.y);
;             f32x2 av0 = {a0, a0}, av1 = {a1, a1}, vv0 = {vv.x, vv.x}, vv1 = {vv.y, vv.y};
;             S0[0] += vv0 * kp0.lo; S0[1] += vv0 * kp0.hi; S0[2] += vv0 * kp1.lo; S0[3] += vv0 * kp1.hi;
;             S1[0] += vv1 * kp0.lo; S1[1] += vv1 * kp0.hi; S1[2] += vv1 * kp1.lo; S1[3] += vv1 * kp1.hi;
;             S0[0] += av0 * ka0.lo; S0[1] += av0 * ka0.hi; S0[2] += av0 * ka1.lo; S0[3] += av0 * ka1.hi;
;             S1[0] += av1 * ka0.lo; S1[1] += av1 * ka0.hi; S1[2] += av1 * ka1.lo; S1[3] += av1 * ka1.hi;
;             float y0 = p0 + a0 * cc.x + vv.x * cc.y;
;             float y1 = p1 + a1 * cc.x + vv.y * cc.y;
;             ka0 = *reinterpret_cast<const f32x4*>(qn + 6144); ka1 = *reinterpret_cast<const f32x4*>(qn + 6144 + 4);
;             kp0 = *reinterpret_cast<const f32x4*>(qn + 8192); kp1 = *reinterpret_cast<const f32x4*>(qn + 8192 + 4);
;             vv = *reinterpret_cast<const f32x2*>(B + 10240 + sn * 64 + row0);
;             cc = *reinterpret_cast<const f32x2*>(B + 14336 + sn * 4);
;             yk0 += ym[jj] * y0; yk1 += ym[jj] * y1;
;           }
.Lsc_loop:
	s_waitcnt lgkmcnt(0)
	ds_read_b128 v[56:59], v200 offset:256
	ds_read_b128 v[60:63], v200 offset:272
	ds_read_b128 v[64:67], v200 offset:8448
	ds_read_b128 v[68:71], v200 offset:8464
	ds_read_b128 v[72:75], v200 offset:24832
	ds_read_b128 v[76:79], v200 offset:24848
	ds_read_b128 v[80:83], v200 offset:33024
	ds_read_b128 v[84:87], v200 offset:33040
	ds_read_b64 v[244:245], v201 offset:41216
	ds_read_b64 v[246:247], v202 offset:57360
	v_pk_mul_f32 v[250:251], v[0:1], v[208:209] op_sel_hi:[1,0]
	v_pk_mul_f32 v[252:253], v[0:1], v[216:217] op_sel_hi:[1,0]
	v_pk_fma_f32 v[250:251], v[2:3], v[208:209], v[250:251] op_sel:[0,1,0]
	v_pk_fma_f32 v[252:253], v[2:3], v[216:217], v[252:253] op_sel:[0,1,0]
	v_pk_fma_f32 v[250:251], v[4:5], v[210:211], v[250:251] op_sel_hi:[1,0,1]
	v_pk_fma_f32 v[252:253], v[4:5], v[218:219], v[252:253] op_sel_hi:[1,0,1]
	v_pk_fma_f32 v[250:251], v[6:7], v[210:211], v[250:251] op_sel:[0,1,0]
	v_pk_fma_f32 v[252:253], v[6:7], v[218:219], v[252:253] op_sel:[0,1,0]
	v_pk_fma_f32 v[250:251], v[8:9], v[212:213], v[250:251] op_sel_hi:[1,0,1]
	v_pk_fma_f32 v[252:253], v[8:9], v[220:221], v[252:253] op_sel_hi:[1,0,1]
	v_pk_fma_f32 v[250:251], v[10:11], v[212:213], v[250:251] op_sel:[0,1,0]
	v_pk_fma_f32 v[252:253], v[10:11], v[220:221], v[252:253] op_sel:[0,1,0]
	v_pk_fma_f32 v[250:251], v[12:13], v[214:215], v[250:251] op_sel_hi:[1,0,1]
	v_pk_fma_f32 v[252:253], v[12:13], v[222:223], v[252:253] op_sel_hi:[1,0,1]
	v_pk_fma_f32 v[250:251], v[14:15], v[214:215], v[250:251] op_sel:[0,1,0]
	v_pk_fma_f32 v[252:253], v[14:15], v[222:223], v[252:253] op_sel:[0,1,0]
	v_pk_fma_f32 v[0:1], v[240:241], v[232:233], v[0:1] op_sel_hi:[1,0,1]
	v_add_f32_dpp v250, v250, v250 quad_perm:[1,0,3,2] row_mask:0xf bank_mask:0xf bound_ctrl:1
	v_pk_fma_f32 v[2:3], v[240:241], v[232:233], v[2:3] op_sel:[0,1,0]
	v_add_f32_dpp v251, v251, v251 quad_perm:[1,0,3,2] row_mask:0xf bank_mask:0xf bound_ctrl:1
	v_pk_fma_f32 v[4:5], v[240:241], v[234:235], v[4:5] op_sel_hi:[1,0,1]
	v_add_f32_dpp v250, v250, v250 quad_perm:[2,3,0,1] row_mask:0xf bank_mask:0xf bound_ctrl:1
	v_pk_fma_f32 v[6:7], v[240:241], v[234:235], v[6:7] op_sel:[0,1,0]
	v_add_f32_dpp v251, v251, v251 quad_perm:[2,3,0,1] row_mask:0xf bank_mask:0xf bound_ctrl:1
	v_pk_fma_f32 v[8:9], v[240:241], v[236:237], v[8:9] op_sel_hi:[1,0,1]
	v_add_f32_dpp v250, v250, v250 row_half_mirror row_mask:0xf bank_mask:0xf bound_ctrl:1
	v_pk_fma_f32 v[10:11], v[240:241], v[236:237], v[10:11] op_sel:[0,1,0]
	v_add_f32_dpp v251, v251, v251 row_half_mirror row_mask:0xf bank_mask:0xf bound_ctrl:1
	v_pk_fma_f32 v[12:13], v[240:241], v[238:239], v[12:13] op_sel_hi:[1,0,1]
	v_pk_fma_f32 v[14:15], v[240:241], v[238:239], v[14:15] op_sel:[0,1,0]
	v_pk_fma_f32 v[0:1], v[250:251], v[224:225], v[0:1] op_sel_hi:[1,0,1]
	v_add_f32_dpp v252, v252, v252 quad_perm:[1,0,3,2] row_mask:0xf bank_mask:0xf bound_ctrl:1
	v_pk_fma_f32 v[2:3], v[250:251], v[224:225], v[2:3] op_sel:[0,1,0]
	v_add_f32_dpp v253, v253, v253 quad_perm:[1,0,3,2] row_mask:0xf bank_mask:0xf bound_ctrl:1
	v_pk_fma_f32 v[4:5], v[250:251], v[226:227], v[4:5] op_sel_hi:[1,0,1]
	v_add_f32_dpp v252, v252, v252 quad_perm:[2,3,0,1] row_mask:0xf bank_mask:0xf bound_ctrl:1
	v_pk_fma_f32 v[6:7], v[250:251], v[226:227], v[6:7] op_sel:[0,1,0]
	v_add_f32_dpp v253, v253, v253 quad_perm:[2,3,0,1] row_mask:0xf bank_mask:0xf bound_ctrl:1
	v_pk_fma_f32 v[8:9], v[250:251], v[228:229], v[8:9] op_sel_hi:[1,0,1]
	v_add_f32_dpp v252, v252, v252 row_half_mirror row_mask:0xf bank_mask:0xf bound_ctrl:1
	v_pk_fma_f32 v[10:11], v[250:251], v[228:229], v[10:11] op_sel:[0,1,0]
	v_add_f32_dpp v253, v253, v253 row_half_mirror row_mask:0xf bank_mask:0xf bound_ctrl:1
	v_pk_fma_f32 v[12:13], v[250:251], v[230:231], v[12:13] op_sel_hi:[1,0,1]
	v_pk_fma_f32 v[14:15], v[250:251], v[230:231], v[14:15] op_sel:[0,1,0]
	v_pk_fma_f32 v[248:249], v[250:251], v[242:243], v[252:253] op_sel_hi:[1,0,1]
	v_pk_fma_f32 v[248:249], v[240:241], v[242:243], v[248:249] op_sel:[0,1,0]
	s_mov_b64 exec, s[98:99]
	ds_write_b64 v201, v[248:249] offset:49152
	s_mov_b64 exec, -1
	s_waitcnt lgkmcnt(1)
	ds_read_b128 v[208:211], v200 offset:512
	ds_read_b128 v[212:215], v200 offset:528
	ds_read_b128 v[216:219], v200 offset:8704
	ds_read_b128 v[220:223], v200 offset:8720
	ds_read_b128 v[224:227], v200 offset:25088
	ds_read_b128 v[228:231], v200 offset:25104
	ds_read_b128 v[232:235], v200 offset:33280
	ds_read_b128 v[236:239], v200 offset:33296
	ds_read_b64 v[240:241], v201 offset:41472
	ds_read_b64 v[242:243], v202 offset:57376
	v_pk_mul_f32 v[250:251], v[0:1], v[56:57] op_sel_hi:[1,0]
	v_pk_mul_f32 v[252:253], v[0:1], v[64:65] op_sel_hi:[1,0]
	v_pk_fma_f32 v[250:251], v[2:3], v[56:57], v[250:251] op_sel:[0,1,0]
	v_pk_fma_f32 v[252:253], v[2:3], v[64:65], v[252:253] op_sel:[0,1,0]
	v_pk_fma_f32 v[250:251], v[4:5], v[58:59], v[250:251] op_sel_hi:[1,0,1]
	v_pk_fma_f32 v[252:253], v[4:5], v[66:67], v[252:253] op_sel_hi:[1,0,1]
	v_pk_fma_f32 v[250:251], v[6:7], v[58:59], v[250:251] op_sel:[0,1,0]
	v_pk_fma_f32 v[252:253], v[6:7], v[66:67], v[252:253] op_sel:[0,1,0]
	v_pk_fma_f32 v[250:251], v[8:9], v[60:61], v[250:251] op_sel_hi:[1,0,1]
	v_pk_fma_f32 v[252:253], v[8:9], v[68:69], v[252:253] op_sel_hi:[1,0,1]
	v_pk_fma_f32 v[250:251], v[10:11], v[60:61], v[250:251] op_sel:[0,1,0]
	v_pk_fma_f32 v[252:253], v[10:11], v[68:69], v[252:253] op_sel:[0,1,0]
	v_pk_fma_f32 v[250:251], v[12:13], v[62:63], v[250:251] op_sel_hi:[1,0,1]
	v_pk_fma_f32 v[252:253], v[12:13], v[70:71], v[252:253] op_sel_hi:[1,0,1]
	v_pk_fma_f32 v[250:251], v[14:15], v[62:63], v[250:251] op_sel:[0,1,0]
	v_pk_fma_f32 v[252:253], v[14:15], v[70:71], v[252:253] op_sel:[0,1,0]
; __device__ __forceinline__ void phase_scan(const Params& p, int bid, int nblk, int wv) {
;     ...
;           for (int jj = 0; jj < 8; ++jj) {
;             const int s = sb * 8 + jj;
;             const int sn = (s + 1) & 31;
;             const float* qn = q + sn * 64;
;             f32x2 sa0 = S0[0] * kkn0.lo, sa1 = S1[0] * kkn0.lo, yp0 = S0[0] * wr0.lo, yp1 = S1[0] * wr0.lo;
;             sa0 += S0[1] * kkn0.hi; sa1 += S1[1] * kkn0.hi; yp0 += S0[1] * wr0.hi; yp1 += S1[1] * wr0.hi;
;             sa0 += S0[2] * kkn1.lo; sa1 += S1[2] * kkn1.lo; yp0 += S0[2] * wr1.lo; yp1 += S1[2] * wr1.lo;
;             sa0 += S0[3] * kkn1.hi; sa1 += S1[3] * kkn1.hi; yp0 += S0[3] * wr1.hi; yp1 += S1[3] * wr1.hi;
;             kkn0 = *reinterpret_cast<const f32x4*>(qn); kkn1 = *reinterpret_cast<const f32x4*>(qn + 4);
;             wr0 = *reinterpret_cast<const f32x4*>(qn + 2048); wr1 = *reinterpret_cast<const f32x4*>(qn + 2048 + 4);
;             float a0 = reduce8_np(sa0.x + sa0.y), p0 = reduce8_np(yp0.x + yp0.y);
;             float a1 = reduce8_np(sa1.x + sa1.y), p1 = reduce8_np(yp1.x + yp1.y);
;             f32x2 av0 = {a0, a0}, av1 = {a1, a1}, vv0 = {vv.x, vv.x}, vv1 = {vv.y, vv.y};
;             S0[0] += vv0 * kp0.lo; S0[1] += vv0 * kp0.hi; S0[2] += vv0 * kp1.lo; S0[3] += vv0 * kp1.hi;
;             S1[0] += vv1 * kp0.lo; S1[1] += vv1 * kp0.hi; S1[2] += vv1 * kp1.lo; S1[3] += vv1 * kp1.hi;
;             S0[0] += av0 * ka0.lo; S0[1] += av0 * ka0.hi; S0[2] += av0 * ka1.lo; S0[3] += av0 * ka1.hi;
;             S1[0] += av1 * ka0.lo; S1[1] += av1 * ka0.hi; S1[2] += av1 * ka1.lo; S1[3] += av1 * ka1.hi;
;             float y0 = p0 + a0 * cc.x + vv.x * cc.y;
;             float y1 = p1 + a1 * cc.x + vv.y * cc.y;
;             ka0 = *reinterpret_cast<const f32x4*>(qn + 6144); ka1 = *reinterpret_cast<const f32x4*>(qn + 6144 + 4);
;             kp0 = *reinterpret_cast<const f32x4*>(qn + 8192); kp1 = *reinterpret_cast<const f32x4*>(qn + 8192 + 4);
;             vv = *reinterpret_cast<const f32x2*>(B + 10240 + sn * 64 + row0);
;             cc = *reinterpret_cast<const f32x2*>(B + 14336 + sn * 4);
;             yk0 += ym[jj] * y0; yk1 += ym[jj] * y1;
;           }
	v_pk_fma_f32 v[0:1], v[244:245], v[80:81], v[0:1] op_sel_hi:[1,0,1]
	v_add_f32_dpp v250, v250, v250 quad_perm:[1,0,3,2] row_mask:0xf bank_mask:0xf bound_ctrl:1
	v_pk_fma_f32 v[2:3], v[244:245], v[80:81], v[2:3] op_sel:[0,1,0]
	v_add_f32_dpp v251, v251, v251 quad_perm:[1,0,3,2] row_mask:0xf bank_mask:0xf bound_ctrl:1
	v_pk_fma_f32 v[4:5], v[244:245], v[82:83], v[4:5] op_sel_hi:[1,0,1]
	v_add_f32_dpp v250, v250, v250 quad_perm:[2,3,0,1] row_mask:0xf bank_mask:0xf bound_ctrl:1
	v_pk_fma_f32 v[6:7], v[244:245], v[82:83], v[6:7] op_sel:[0,1,0]
	v_add_f32_dpp v251, v251, v251 quad_perm:[2,3,0,1] row_mask:0xf bank_mask:0xf bound_ctrl:1
	v_pk_fma_f32 v[8:9], v[244:245], v[84:85], v[8:9] op_sel_hi:[1,0,1]
	v_add_f32_dpp v250, v250, v250 row_half_mirror row_mask:0xf bank_mask:0xf bound_ctrl:1
	v_pk_fma_f32 v[10:11], v[244:245], v[84:85], v[10:11] op_sel:[0,1,0]
	v_add_f32_dpp v251, v251, v251 row_half_mirror row_mask:0xf bank_mask:0xf bound_ctrl:1
	v_pk_fma_f32 v[12:13], v[244:245], v[86:87], v[12:13] op_sel_hi:[1,0,1]
	v_pk_fma_f32 v[14:15], v[244:245], v[86:87], v[14:15] op_sel:[0,1,0]
	v_pk_fma_f32 v[0:1], v[250:251], v[72:73], v[0:1] op_sel_hi:[1,0,1]
	v_add_f32_dpp v252, v252, v252 quad_perm:[1,0,3,2] row_mask:0xf bank_mask:0xf bound_ctrl:1
	v_pk_fma_f32 v[2:3], v[250:251], v[72:73], v[2:3] op_sel:[0,1,0]
	v_add_f32_dpp v253, v253, v253 quad_perm:[1,0,3,2] row_mask:0xf bank_mask:0xf bound_ctrl:1
	v_pk_fma_f32 v[4:5], v[250:251], v[74:75], v[4:5] op_sel_hi:[1,0,1]
	v_add_f32_dpp v252, v252, v252 quad_perm:[2,3,0,1] row_mask:0xf bank_mask:0xf bound_ctrl:1
	v_pk_fma_f32 v[6:7], v[250:251], v[74:75], v[6:7] op_sel:[0,1,0]
	v_add_f32_dpp v253, v253, v253 quad_perm:[2,3,0,1] row_mask:0xf bank_mask:0xf bound_ctrl:1
	v_pk_fma_f32 v[8:9], v[250:251], v[76:77], v[8:9] op_sel_hi:[1,0,1]
	v_add_f32_dpp v252, v252, v252 row_half_mirror row_mask:0xf bank_mask:0xf bound_ctrl:1
	v_pk_fma_f32 v[10:11], v[250:251], v[76:77], v[10:11] op_sel:[0,1,0]
	v_add_f32_dpp v253, v253, v253 row_half_mirror row_mask:0xf bank_mask:0xf bound_ctrl:1
	v_pk_fma_f32 v[12:13], v[250:251], v[78:79], v[12:13] op_sel_hi:[1,0,1]
	v_pk_fma_f32 v[14:15], v[250:251], v[78:79], v[14:15] op_sel:[0,1,0]
	v_pk_fma_f32 v[248:249], v[250:251], v[246:247], v[252:253] op_sel_hi:[1,0,1]
	v_pk_fma_f32 v[248:249], v[244:245], v[246:247], v[248:249] op_sel:[0,1,0]
	s_mov_b64 exec, s[98:99]
	ds_write_b64 v201, v[248:249] offset:49408
	s_mov_b64 exec, -1
	s_waitcnt lgkmcnt(1)
	ds_read_b128 v[56:59], v200 offset:768
	ds_read_b128 v[60:63], v200 offset:784
	ds_read_b128 v[64:67], v200 offset:8960
	ds_read_b128 v[68:71], v200 offset:8976
	ds_read_b128 v[72:75], v200 offset:25344
	ds_read_b128 v[76:79], v200 offset:25360
	ds_read_b128 v[80:83], v200 offset:33536
	ds_read_b128 v[84:87], v200 offset:33552
	ds_read_b64 v[244:245], v201 offset:41728
	ds_read_b64 v[246:247], v202 offset:57392
	v_pk_mul_f32 v[250:251], v[0:1], v[208:209] op_sel_hi:[1,0]
	v_pk_mul_f32 v[252:253], v[0:1], v[216:217] op_sel_hi:[1,0]
	v_pk_fma_f32 v[250:251], v[2:3], v[208:209], v[250:251] op_sel:[0,1,0]
	v_pk_fma_f32 v[252:253], v[2:3], v[216:217], v[252:253] op_sel:[0,1,0]
	v_pk_fma_f32 v[250:251], v[4:5], v[210:211], v[250:251] op_sel_hi:[1,0,1]
	v_pk_fma_f32 v[252:253], v[4:5], v[218:219], v[252:253] op_sel_hi:[1,0,1]
	v_pk_fma_f32 v[250:251], v[6:7], v[210:211], v[250:251] op_sel:[0,1,0]
	v_pk_fma_f32 v[252:253], v[6:7], v[218:219], v[252:253] op_sel:[0,1,0]
	v_pk_fma_f32 v[250:251], v[8:9], v[212:213], v[250:251] op_sel_hi:[1,0,1]
	v_pk_fma_f32 v[252:253], v[8:9], v[220:221], v[252:253] op_sel_hi:[1,0,1]
	v_pk_fma_f32 v[250:251], v[10:11], v[212:213], v[250:251] op_sel:[0,1,0]
	v_pk_fma_f32 v[252:253], v[10:11], v[220:221], v[252:253] op_sel:[0,1,0]
	v_pk_fma_f32 v[250:251], v[12:13], v[214:215], v[250:251] op_sel_hi:[1,0,1]
	v_pk_fma_f32 v[252:253], v[12:13], v[222:223], v[252:253] op_sel_hi:[1,0,1]
	v_pk_fma_f32 v[250:251], v[14:15], v[214:215], v[250:251] op_sel:[0,1,0]
	v_pk_fma_f32 v[252:253], v[14:15], v[222:223], v[252:253] op_sel:[0,1,0]
	v_pk_fma_f32 v[0:1], v[240:241], v[232:233], v[0:1] op_sel_hi:[1,0,1]
	v_add_f32_dpp v250, v250, v250 quad_perm:[1,0,3,2] row_mask:0xf bank_mask:0xf bound_ctrl:1
	v_pk_fma_f32 v[2:3], v[240:241], v[232:233], v[2:3] op_sel:[0,1,0]
	v_add_f32_dpp v251, v251, v251 quad_perm:[1,0,3,2] row_mask:0xf bank_mask:0xf bound_ctrl:1
	v_pk_fma_f32 v[4:5], v[240:241], v[234:235], v[4:5] op_sel_hi:[1,0,1]
	v_add_f32_dpp v250, v250, v250 quad_perm:[2,3,0,1] row_mask:0xf bank_mask:0xf bound_ctrl:1
	v_pk_fma_f32 v[6:7], v[240:241], v[234:235], v[6:7] op_sel:[0,1,0]
	v_add_f32_dpp v251, v251, v251 quad_perm:[2,3,0,1] row_mask:0xf bank_mask:0xf bound_ctrl:1
	v_pk_fma_f32 v[8:9], v[240:241], v[236:237], v[8:9] op_sel_hi:[1,0,1]
	v_add_f32_dpp v250, v250, v250 row_half_mirror row_mask:0xf bank_mask:0xf bound_ctrl:1
	v_pk_fma_f32 v[10:11], v[240:241], v[236:237], v[10:11] op_sel:[0,1,0]
	v_add_f32_dpp v251, v251, v251 row_half_mirror row_mask:0xf bank_mask:0xf bound_ctrl:1
	v_pk_fma_f32 v[12:13], v[240:241], v[238:239], v[12:13] op_sel_hi:[1,0,1]
	v_pk_fma_f32 v[14:15], v[240:241], v[238:239], v[14:15] op_sel:[0,1,0]
	v_pk_fma_f32 v[0:1], v[250:251], v[224:225], v[0:1] op_sel_hi:[1,0,1]
	v_add_f32_dpp v252, v252, v252 quad_perm:[1,0,3,2] row_mask:0xf bank_mask:0xf bound_ctrl:1
	v_pk_fma_f32 v[2:3], v[250:251], v[224:225], v[2:3] op_sel:[0,1,0]
	v_add_f32_dpp v253, v253, v253 quad_perm:[1,0,3,2] row_mask:0xf bank_mask:0xf bound_ctrl:1
	v_pk_fma_f32 v[4:5], v[250:251], v[226:227], v[4:5] op_sel_hi:[1,0,1]
	v_add_f32_dpp v252, v252, v252 quad_perm:[2,3,0,1] row_mask:0xf bank_mask:0xf bound_ctrl:1
	v_pk_fma_f32 v[6:7], v[250:251], v[226:227], v[6:7] op_sel:[0,1,0]
	v_add_f32_dpp v253, v253, v253 quad_perm:[2,3,0,1] row_mask:0xf bank_mask:0xf bound_ctrl:1
	v_pk_fma_f32 v[8:9], v[250:251], v[228:229], v[8:9] op_sel_hi:[1,0,1]
	v_add_f32_dpp v252, v252, v252 row_half_mirror row_mask:0xf bank_mask:0xf bound_ctrl:1
	v_pk_fma_f32 v[10:11], v[250:251], v[228:229], v[10:11] op_sel:[0,1,0]
	v_add_f32_dpp v253, v253, v253 row_half_mirror row_mask:0xf bank_mask:0xf bound_ctrl:1
	v_pk_fma_f32 v[12:13], v[250:251], v[230:231], v[12:13] op_sel_hi:[1,0,1]
	v_pk_fma_f32 v[14:15], v[250:251], v[230:231], v[14:15] op_sel:[0,1,0]
	v_pk_fma_f32 v[248:249], v[250:251], v[242:243], v[252:253] op_sel_hi:[1,0,1]
	v_pk_fma_f32 v[248:249], v[240:241], v[242:243], v[248:249] op_sel:[0,1,0]
	s_mov_b64 exec, s[98:99]
	ds_write_b64 v201, v[248:249] offset:49664
	s_mov_b64 exec, -1
	s_waitcnt lgkmcnt(1)
; __device__ __forceinline__ void phase_scan(const Params& p, int bid, int nblk, int wv) {
;     ...
;           for (int jj = 0; jj < 8; ++jj) {
;             const int s = sb * 8 + jj;
;             const int sn = (s + 1) & 31;
;             const float* qn = q + sn * 64;
;             f32x2 sa0 = S0[0] * kkn0.lo, sa1 = S1[0] * kkn0.lo, yp0 = S0[0] * wr0.lo, yp1 = S1[0] * wr0.lo;
;             sa0 += S0[1] * kkn0.hi; sa1 += S1[1] * kkn0.hi; yp0 += S0[1] * wr0.hi; yp1 += S1[1] * wr0.hi;
;             sa0 += S0[2] * kkn1.lo; sa1 += S1[2] * kkn1.lo; yp0 += S0[2] * wr1.lo; yp1 += S1[2] * wr1.lo;
;             sa0 += S0[3] * kkn1.hi; sa1 += S1[3] * kkn1.hi; yp0 += S0[3] * wr1.hi; yp1 += S1[3] * wr1.hi;
;             kkn0 = *reinterpret_cast<const f32x4*>(qn); kkn1 = *reinterpret_cast<const f32x4*>(qn + 4);
;             wr0 = *reinterpret_cast<const f32x4*>(qn + 2048); wr1 = *reinterpret_cast<const f32x4*>(qn + 2048 + 4);
;             float a0 = reduce8_np(sa0.x + sa0.y), p0 = reduce8_np(yp0.x + yp0.y);
;             float a1 = reduce8_np(sa1.x + sa1.y), p1 = reduce8_np(yp1.x + yp1.y);
;             f32x2 av0 = {a0, a0}, av1 = {a1, a1}, vv0 = {vv.x, vv.x}, vv1 = {vv.y, vv.y};
;             S0[0] += vv0 * kp0.lo; S0[1] += vv0 * kp0.hi; S0[2] += vv0 * kp1.lo; S0[3] += vv0 * kp1.hi;
;             S1[0] += vv1 * kp0.lo; S1[1] += vv1 * kp0.hi; S1[2] += vv1 * kp1.lo; S1[3] += vv1 * kp1.hi;
;             S0[0] += av0 * ka0.lo; S0[1] += av0 * ka0.hi; S0[2] += av0 * ka1.lo; S0[3] += av0 * ka1.hi;
;             S1[0] += av1 * ka0.lo; S1[1] += av1 * ka0.hi; S1[2] += av1 * ka1.lo; S1[3] += av1 * ka1.hi;
;             float y0 = p0 + a0 * cc.x + vv.x * cc.y;
;             float y1 = p1 + a1 * cc.x + vv.y * cc.y;
;             ka0 = *reinterpret_cast<const f32x4*>(qn + 6144); ka1 = *reinterpret_cast<const f32x4*>(qn + 6144 + 4);
;             kp0 = *reinterpret_cast<const f32x4*>(qn + 8192); kp1 = *reinterpret_cast<const f32x4*>(qn + 8192 + 4);
;             vv = *reinterpret_cast<const f32x2*>(B + 10240 + sn * 64 + row0);
;             cc = *reinterpret_cast<const f32x2*>(B + 14336 + sn * 4);
;             yk0 += ym[jj] * y0; yk1 += ym[jj] * y1;
;           }
	ds_read_b128 v[208:211], v200 offset:1024
	ds_read_b128 v[212:215], v200 offset:1040
	ds_read_b128 v[216:219], v200 offset:9216
	ds_read_b128 v[220:223], v200 offset:9232
	ds_read_b128 v[224:227], v200 offset:25600
	ds_read_b128 v[228:231], v200 offset:25616
	ds_read_b128 v[232:235], v200 offset:33792
	ds_read_b128 v[236:239], v200 offset:33808
	ds_read_b64 v[240:241], v201 offset:41984
	ds_read_b64 v[242:243], v202 offset:57408
	v_pk_mul_f32 v[250:251], v[0:1], v[56:57] op_sel_hi:[1,0]
	v_pk_mul_f32 v[252:253], v[0:1], v[64:65] op_sel_hi:[1,0]
	v_pk_fma_f32 v[250:251], v[2:3], v[56:57], v[250:251] op_sel:[0,1,0]
	v_pk_fma_f32 v[252:253], v[2:3], v[64:65], v[252:253] op_sel:[0,1,0]
	v_pk_fma_f32 v[250:251], v[4:5], v[58:59], v[250:251] op_sel_hi:[1,0,1]
	v_pk_fma_f32 v[252:253], v[4:5], v[66:67], v[252:253] op_sel_hi:[1,0,1]
	v_pk_fma_f32 v[250:251], v[6:7], v[58:59], v[250:251] op_sel:[0,1,0]
	v_pk_fma_f32 v[252:253], v[6:7], v[66:67], v[252:253] op_sel:[0,1,0]
	v_pk_fma_f32 v[250:251], v[8:9], v[60:61], v[250:251] op_sel_hi:[1,0,1]
	v_pk_fma_f32 v[252:253], v[8:9], v[68:69], v[252:253] op_sel_hi:[1,0,1]
	v_pk_fma_f32 v[250:251], v[10:11], v[60:61], v[250:251] op_sel:[0,1,0]
	v_pk_fma_f32 v[252:253], v[10:11], v[68:69], v[252:253] op_sel:[0,1,0]
	v_pk_fma_f32 v[250:251], v[12:13], v[62:63], v[250:251] op_sel_hi:[1,0,1]
	v_pk_fma_f32 v[252:253], v[12:13], v[70:71], v[252:253] op_sel_hi:[1,0,1]
	v_pk_fma_f32 v[250:251], v[14:15], v[62:63], v[250:251] op_sel:[0,1,0]
	v_pk_fma_f32 v[252:253], v[14:15], v[70:71], v[252:253] op_sel:[0,1,0]
	v_pk_fma_f32 v[0:1], v[244:245], v[80:81], v[0:1] op_sel_hi:[1,0,1]
	v_add_f32_dpp v250, v250, v250 quad_perm:[1,0,3,2] row_mask:0xf bank_mask:0xf bound_ctrl:1
	v_pk_fma_f32 v[2:3], v[244:245], v[80:81], v[2:3] op_sel:[0,1,0]
	v_add_f32_dpp v251, v251, v251 quad_perm:[1,0,3,2] row_mask:0xf bank_mask:0xf bound_ctrl:1
	v_pk_fma_f32 v[4:5], v[244:245], v[82:83], v[4:5] op_sel_hi:[1,0,1]
	v_add_f32_dpp v250, v250, v250 quad_perm:[2,3,0,1] row_mask:0xf bank_mask:0xf bound_ctrl:1
	v_pk_fma_f32 v[6:7], v[244:245], v[82:83], v[6:7] op_sel:[0,1,0]
	v_add_f32_dpp v251, v251, v251 quad_perm:[2,3,0,1] row_mask:0xf bank_mask:0xf bound_ctrl:1
	v_pk_fma_f32 v[8:9], v[244:245], v[84:85], v[8:9] op_sel_hi:[1,0,1]
	v_add_f32_dpp v250, v250, v250 row_half_mirror row_mask:0xf bank_mask:0xf bound_ctrl:1
	v_pk_fma_f32 v[10:11], v[244:245], v[84:85], v[10:11] op_sel:[0,1,0]
	v_add_f32_dpp v251, v251, v251 row_half_mirror row_mask:0xf bank_mask:0xf bound_ctrl:1
	v_pk_fma_f32 v[12:13], v[244:245], v[86:87], v[12:13] op_sel_hi:[1,0,1]
	v_pk_fma_f32 v[14:15], v[244:245], v[86:87], v[14:15] op_sel:[0,1,0]
	v_pk_fma_f32 v[0:1], v[250:251], v[72:73], v[0:1] op_sel_hi:[1,0,1]
	v_add_f32_dpp v252, v252, v252 quad_perm:[1,0,3,2] row_mask:0xf bank_mask:0xf bound_ctrl:1
	v_pk_fma_f32 v[2:3], v[250:251], v[72:73], v[2:3] op_sel:[0,1,0]
	v_add_f32_dpp v253, v253, v253 quad_perm:[1,0,3,2] row_mask:0xf bank_mask:0xf bound_ctrl:1
	v_pk_fma_f32 v[4:5], v[250:251], v[74:75], v[4:5] op_sel_hi:[1,0,1]
	v_add_f32_dpp v252, v252, v252 quad_perm:[2,3,0,1] row_mask:0xf bank_mask:0xf bound_ctrl:1
	v_pk_fma_f32 v[6:7], v[250:251], v[74:75], v[6:7] op_sel:[0,1,0]
	v_add_f32_dpp v253, v253, v253 quad_perm:[2,3,0,1] row_mask:0xf bank_mask:0xf bound_ctrl:1
	v_pk_fma_f32 v[8:9], v[250:251], v[76:77], v[8:9] op_sel_hi:[1,0,1]
	v_add_f32_dpp v252, v252, v252 row_half_mirror row_mask:0xf bank_mask:0xf bound_ctrl:1
	v_pk_fma_f32 v[10:11], v[250:251], v[76:77], v[10:11] op_sel:[0,1,0]
	v_add_f32_dpp v253, v253, v253 row_half_mirror row_mask:0xf bank_mask:0xf bound_ctrl:1
	v_pk_fma_f32 v[12:13], v[250:251], v[78:79], v[12:13] op_sel_hi:[1,0,1]
	v_pk_fma_f32 v[14:15], v[250:251], v[78:79], v[14:15] op_sel:[0,1,0]
	v_pk_fma_f32 v[248:249], v[250:251], v[246:247], v[252:253] op_sel_hi:[1,0,1]
	v_pk_fma_f32 v[248:249], v[244:245], v[246:247], v[248:249] op_sel:[0,1,0]
	s_mov_b64 exec, s[98:99]
	ds_write_b64 v201, v[248:249] offset:49920
	s_mov_b64 exec, -1
	s_waitcnt lgkmcnt(1)
	ds_read_b128 v[56:59], v200 offset:1280
	ds_read_b128 v[60:63], v200 offset:1296
	ds_read_b128 v[64:67], v200 offset:9472
	ds_read_b128 v[68:71], v200 offset:9488
	ds_read_b128 v[72:75], v200 offset:25856
	ds_read_b128 v[76:79], v200 offset:25872
	ds_read_b128 v[80:83], v200 offset:34048
	ds_read_b128 v[84:87], v200 offset:34064
	ds_read_b64 v[244:245], v201 offset:42240
	ds_read_b64 v[246:247], v202 offset:57424
	v_pk_mul_f32 v[250:251], v[0:1], v[208:209] op_sel_hi:[1,0]
	v_pk_mul_f32 v[252:253], v[0:1], v[216:217] op_sel_hi:[1,0]
	v_pk_fma_f32 v[250:251], v[2:3], v[208:209], v[250:251] op_sel:[0,1,0]
	v_pk_fma_f32 v[252:253], v[2:3], v[216:217], v[252:253] op_sel:[0,1,0]
	v_pk_fma_f32 v[250:251], v[4:5], v[210:211], v[250:251] op_sel_hi:[1,0,1]
	v_pk_fma_f32 v[252:253], v[4:5], v[218:219], v[252:253] op_sel_hi:[1,0,1]
	v_pk_fma_f32 v[250:251], v[6:7], v[210:211], v[250:251] op_sel:[0,1,0]
	v_pk_fma_f32 v[252:253], v[6:7], v[218:219], v[252:253] op_sel:[0,1,0]
	v_pk_fma_f32 v[250:251], v[8:9], v[212:213], v[250:251] op_sel_hi:[1,0,1]
	v_pk_fma_f32 v[252:253], v[8:9], v[220:221], v[252:253] op_sel_hi:[1,0,1]
	v_pk_fma_f32 v[250:251], v[10:11], v[212:213], v[250:251] op_sel:[0,1,0]
	v_pk_fma_f32 v[252:253], v[10:11], v[220:221], v[252:253] op_sel:[0,1,0]
	v_pk_fma_f32 v[250:251], v[12:13], v[214:215], v[250:251] op_sel_hi:[1,0,1]
	v_pk_fma_f32 v[252:253], v[12:13], v[222:223], v[252:253] op_sel_hi:[1,0,1]
	v_pk_fma_f32 v[250:251], v[14:15], v[214:215], v[250:251] op_sel:[0,1,0]
	v_pk_fma_f32 v[252:253], v[14:15], v[222:223], v[252:253] op_sel:[0,1,0]
	v_pk_fma_f32 v[0:1], v[240:241], v[232:233], v[0:1] op_sel_hi:[1,0,1]
; __device__ __forceinline__ void phase_scan(const Params& p, int bid, int nblk, int wv) {
;     ...
;           for (int jj = 0; jj < 8; ++jj) {
;             const int s = sb * 8 + jj;
;             const int sn = (s + 1) & 31;
;             const float* qn = q + sn * 64;
;             f32x2 sa0 = S0[0] * kkn0.lo, sa1 = S1[0] * kkn0.lo, yp0 = S0[0] * wr0.lo, yp1 = S1[0] * wr0.lo;
;             sa0 += S0[1] * kkn0.hi; sa1 += S1[1] * kkn0.hi; yp0 += S0[1] * wr0.hi; yp1 += S1[1] * wr0.hi;
;             sa0 += S0[2] * kkn1.lo; sa1 += S1[2] * kkn1.lo; yp0 += S0[2] * wr1.lo; yp1 += S1[2] * wr1.lo;
;             sa0 += S0[3] * kkn1.hi; sa1 += S1[3] * kkn1.hi; yp0 += S0[3] * wr1.hi; yp1 += S1[3] * wr1.hi;
;             kkn0 = *reinterpret_cast<const f32x4*>(qn); kkn1 = *reinterpret_cast<const f32x4*>(qn + 4);
;             wr0 = *reinterpret_cast<const f32x4*>(qn + 2048); wr1 = *reinterpret_cast<const f32x4*>(qn + 2048 + 4);
;             float a0 = reduce8_np(sa0.x + sa0.y), p0 = reduce8_np(yp0.x + yp0.y);
;             float a1 = reduce8_np(sa1.x + sa1.y), p1 = reduce8_np(yp1.x + yp1.y);
;             f32x2 av0 = {a0, a0}, av1 = {a1, a1}, vv0 = {vv.x, vv.x}, vv1 = {vv.y, vv.y};
;             S0[0] += vv0 * kp0.lo; S0[1] += vv0 * kp0.hi; S0[2] += vv0 * kp1.lo; S0[3] += vv0 * kp1.hi;
;             S1[0] += vv1 * kp0.lo; S1[1] += vv1 * kp0.hi; S1[2] += vv1 * kp1.lo; S1[3] += vv1 * kp1.hi;
;             S0[0] += av0 * ka0.lo; S0[1] += av0 * ka0.hi; S0[2] += av0 * ka1.lo; S0[3] += av0 * ka1.hi;
;             S1[0] += av1 * ka0.lo; S1[1] += av1 * ka0.hi; S1[2] += av1 * ka1.lo; S1[3] += av1 * ka1.hi;
;             float y0 = p0 + a0 * cc.x + vv.x * cc.y;
;             float y1 = p1 + a1 * cc.x + vv.y * cc.y;
;             ka0 = *reinterpret_cast<const f32x4*>(qn + 6144); ka1 = *reinterpret_cast<const f32x4*>(qn + 6144 + 4);
;             kp0 = *reinterpret_cast<const f32x4*>(qn + 8192); kp1 = *reinterpret_cast<const f32x4*>(qn + 8192 + 4);
;             vv = *reinterpret_cast<const f32x2*>(B + 10240 + sn * 64 + row0);
;             cc = *reinterpret_cast<const f32x2*>(B + 14336 + sn * 4);
;             yk0 += ym[jj] * y0; yk1 += ym[jj] * y1;
;           }
	v_add_f32_dpp v250, v250, v250 quad_perm:[1,0,3,2] row_mask:0xf bank_mask:0xf bound_ctrl:1
	v_pk_fma_f32 v[2:3], v[240:241], v[232:233], v[2:3] op_sel:[0,1,0]
	v_add_f32_dpp v251, v251, v251 quad_perm:[1,0,3,2] row_mask:0xf bank_mask:0xf bound_ctrl:1
	v_pk_fma_f32 v[4:5], v[240:241], v[234:235], v[4:5] op_sel_hi:[1,0,1]
	v_add_f32_dpp v250, v250, v250 quad_perm:[2,3,0,1] row_mask:0xf bank_mask:0xf bound_ctrl:1
	v_pk_fma_f32 v[6:7], v[240:241], v[234:235], v[6:7] op_sel:[0,1,0]
	v_add_f32_dpp v251, v251, v251 quad_perm:[2,3,0,1] row_mask:0xf bank_mask:0xf bound_ctrl:1
	v_pk_fma_f32 v[8:9], v[240:241], v[236:237], v[8:9] op_sel_hi:[1,0,1]
	v_add_f32_dpp v250, v250, v250 row_half_mirror row_mask:0xf bank_mask:0xf bound_ctrl:1
	v_pk_fma_f32 v[10:11], v[240:241], v[236:237], v[10:11] op_sel:[0,1,0]
	v_add_f32_dpp v251, v251, v251 row_half_mirror row_mask:0xf bank_mask:0xf bound_ctrl:1
	v_pk_fma_f32 v[12:13], v[240:241], v[238:239], v[12:13] op_sel_hi:[1,0,1]
	v_pk_fma_f32 v[14:15], v[240:241], v[238:239], v[14:15] op_sel:[0,1,0]
	v_pk_fma_f32 v[0:1], v[250:251], v[224:225], v[0:1] op_sel_hi:[1,0,1]
	v_add_f32_dpp v252, v252, v252 quad_perm:[1,0,3,2] row_mask:0xf bank_mask:0xf bound_ctrl:1
	v_pk_fma_f32 v[2:3], v[250:251], v[224:225], v[2:3] op_sel:[0,1,0]
	v_add_f32_dpp v253, v253, v253 quad_perm:[1,0,3,2] row_mask:0xf bank_mask:0xf bound_ctrl:1
	v_pk_fma_f32 v[4:5], v[250:251], v[226:227], v[4:5] op_sel_hi:[1,0,1]
	v_add_f32_dpp v252, v252, v252 quad_perm:[2,3,0,1] row_mask:0xf bank_mask:0xf bound_ctrl:1
	v_pk_fma_f32 v[6:7], v[250:251], v[226:227], v[6:7] op_sel:[0,1,0]
	v_add_f32_dpp v253, v253, v253 quad_perm:[2,3,0,1] row_mask:0xf bank_mask:0xf bound_ctrl:1
	v_pk_fma_f32 v[8:9], v[250:251], v[228:229], v[8:9] op_sel_hi:[1,0,1]
	v_add_f32_dpp v252, v252, v252 row_half_mirror row_mask:0xf bank_mask:0xf bound_ctrl:1
	v_pk_fma_f32 v[10:11], v[250:251], v[228:229], v[10:11] op_sel:[0,1,0]
	v_add_f32_dpp v253, v253, v253 row_half_mirror row_mask:0xf bank_mask:0xf bound_ctrl:1
	v_pk_fma_f32 v[12:13], v[250:251], v[230:231], v[12:13] op_sel_hi:[1,0,1]
	v_pk_fma_f32 v[14:15], v[250:251], v[230:231], v[14:15] op_sel:[0,1,0]
	v_pk_fma_f32 v[248:249], v[250:251], v[242:243], v[252:253] op_sel_hi:[1,0,1]
	v_pk_fma_f32 v[248:249], v[240:241], v[242:243], v[248:249] op_sel:[0,1,0]
	s_mov_b64 exec, s[98:99]
	ds_write_b64 v201, v[248:249] offset:50176
	s_mov_b64 exec, -1
	s_waitcnt lgkmcnt(1)
	ds_read_b128 v[208:211], v200 offset:1536
	ds_read_b128 v[212:215], v200 offset:1552
	ds_read_b128 v[216:219], v200 offset:9728
	ds_read_b128 v[220:223], v200 offset:9744
	ds_read_b128 v[224:227], v200 offset:26112
	ds_read_b128 v[228:231], v200 offset:26128
	ds_read_b128 v[232:235], v200 offset:34304
	ds_read_b128 v[236:239], v200 offset:34320
	ds_read_b64 v[240:241], v201 offset:42496
	ds_read_b64 v[242:243], v202 offset:57440
	v_pk_mul_f32 v[250:251], v[0:1], v[56:57] op_sel_hi:[1,0]
	v_pk_mul_f32 v[252:253], v[0:1], v[64:65] op_sel_hi:[1,0]
	v_pk_fma_f32 v[250:251], v[2:3], v[56:57], v[250:251] op_sel:[0,1,0]
	v_pk_fma_f32 v[252:253], v[2:3], v[64:65], v[252:253] op_sel:[0,1,0]
	v_pk_fma_f32 v[250:251], v[4:5], v[58:59], v[250:251] op_sel_hi:[1,0,1]
	v_pk_fma_f32 v[252:253], v[4:5], v[66:67], v[252:253] op_sel_hi:[1,0,1]
	v_pk_fma_f32 v[250:251], v[6:7], v[58:59], v[250:251] op_sel:[0,1,0]
	v_pk_fma_f32 v[252:253], v[6:7], v[66:67], v[252:253] op_sel:[0,1,0]
	v_pk_fma_f32 v[250:251], v[8:9], v[60:61], v[250:251] op_sel_hi:[1,0,1]
	v_pk_fma_f32 v[252:253], v[8:9], v[68:69], v[252:253] op_sel_hi:[1,0,1]
	v_pk_fma_f32 v[250:251], v[10:11], v[60:61], v[250:251] op_sel:[0,1,0]
	v_pk_fma_f32 v[252:253], v[10:11], v[68:69], v[252:253] op_sel:[0,1,0]
	v_pk_fma_f32 v[250:251], v[12:13], v[62:63], v[250:251] op_sel_hi:[1,0,1]
	v_pk_fma_f32 v[252:253], v[12:13], v[70:71], v[252:253] op_sel_hi:[1,0,1]
	v_pk_fma_f32 v[250:251], v[14:15], v[62:63], v[250:251] op_sel:[0,1,0]
	v_pk_fma_f32 v[252:253], v[14:15], v[70:71], v[252:253] op_sel:[0,1,0]
	v_pk_fma_f32 v[0:1], v[244:245], v[80:81], v[0:1] op_sel_hi:[1,0,1]
	v_add_f32_dpp v250, v250, v250 quad_perm:[1,0,3,2] row_mask:0xf bank_mask:0xf bound_ctrl:1
	v_pk_fma_f32 v[2:3], v[244:245], v[80:81], v[2:3] op_sel:[0,1,0]
	v_add_f32_dpp v251, v251, v251 quad_perm:[1,0,3,2] row_mask:0xf bank_mask:0xf bound_ctrl:1
	v_pk_fma_f32 v[4:5], v[244:245], v[82:83], v[4:5] op_sel_hi:[1,0,1]
	v_add_f32_dpp v250, v250, v250 quad_perm:[2,3,0,1] row_mask:0xf bank_mask:0xf bound_ctrl:1
	v_pk_fma_f32 v[6:7], v[244:245], v[82:83], v[6:7] op_sel:[0,1,0]
	v_add_f32_dpp v251, v251, v251 quad_perm:[2,3,0,1] row_mask:0xf bank_mask:0xf bound_ctrl:1
	v_pk_fma_f32 v[8:9], v[244:245], v[84:85], v[8:9] op_sel_hi:[1,0,1]
	v_add_f32_dpp v250, v250, v250 row_half_mirror row_mask:0xf bank_mask:0xf bound_ctrl:1
	v_pk_fma_f32 v[10:11], v[244:245], v[84:85], v[10:11] op_sel:[0,1,0]
	v_add_f32_dpp v251, v251, v251 row_half_mirror row_mask:0xf bank_mask:0xf bound_ctrl:1
	v_pk_fma_f32 v[12:13], v[244:245], v[86:87], v[12:13] op_sel_hi:[1,0,1]
	v_pk_fma_f32 v[14:15], v[244:245], v[86:87], v[14:15] op_sel:[0,1,0]
	v_pk_fma_f32 v[0:1], v[250:251], v[72:73], v[0:1] op_sel_hi:[1,0,1]
	v_add_f32_dpp v252, v252, v252 quad_perm:[1,0,3,2] row_mask:0xf bank_mask:0xf bound_ctrl:1
	v_pk_fma_f32 v[2:3], v[250:251], v[72:73], v[2:3] op_sel:[0,1,0]
	v_add_f32_dpp v253, v253, v253 quad_perm:[1,0,3,2] row_mask:0xf bank_mask:0xf bound_ctrl:1
	v_pk_fma_f32 v[4:5], v[250:251], v[74:75], v[4:5] op_sel_hi:[1,0,1]
	v_add_f32_dpp v252, v252, v252 quad_perm:[2,3,0,1] row_mask:0xf bank_mask:0xf bound_ctrl:1
	v_pk_fma_f32 v[6:7], v[250:251], v[74:75], v[6:7] op_sel:[0,1,0]
	v_add_f32_dpp v253, v253, v253 quad_perm:[2,3,0,1] row_mask:0xf bank_mask:0xf bound_ctrl:1
	v_pk_fma_f32 v[8:9], v[250:251], v[76:77], v[8:9] op_sel_hi:[1,0,1]
	v_add_f32_dpp v252, v252, v252 row_half_mirror row_mask:0xf bank_mask:0xf bound_ctrl:1
	v_pk_fma_f32 v[10:11], v[250:251], v[76:77], v[10:11] op_sel:[0,1,0]
	v_add_f32_dpp v253, v253, v253 row_half_mirror row_mask:0xf bank_mask:0xf bound_ctrl:1
	v_pk_fma_f32 v[12:13], v[250:251], v[78:79], v[12:13] op_sel_hi:[1,0,1]
	v_pk_fma_f32 v[14:15], v[250:251], v[78:79], v[14:15] op_sel:[0,1,0]
	v_pk_fma_f32 v[248:249], v[250:251], v[246:247], v[252:253] op_sel_hi:[1,0,1]
	v_pk_fma_f32 v[248:249], v[244:245], v[246:247], v[248:249] op_sel:[0,1,0]
	s_mov_b64 exec, s[98:99]
	ds_write_b64 v201, v[248:249] offset:50432
	s_mov_b64 exec, -1
	s_waitcnt lgkmcnt(1)
; __device__ __forceinline__ void phase_scan(const Params& p, int bid, int nblk, int wv) {
;     ...
;           for (int jj = 0; jj < 8; ++jj) {
;             const int s = sb * 8 + jj;
;             const int sn = (s + 1) & 31;
;             const float* qn = q + sn * 64;
;             f32x2 sa0 = S0[0] * kkn0.lo, sa1 = S1[0] * kkn0.lo, yp0 = S0[0] * wr0.lo, yp1 = S1[0] * wr0.lo;
;             sa0 += S0[1] * kkn0.hi; sa1 += S1[1] * kkn0.hi; yp0 += S0[1] * wr0.hi; yp1 += S1[1] * wr0.hi;
;             sa0 += S0[2] * kkn1.lo; sa1 += S1[2] * kkn1.lo; yp0 += S0[2] * wr1.lo; yp1 += S1[2] * wr1.lo;
;             sa0 += S0[3] * kkn1.hi; sa1 += S1[3] * kkn1.hi; yp0 += S0[3] * wr1.hi; yp1 += S1[3] * wr1.hi;
;             kkn0 = *reinterpret_cast<const f32x4*>(qn); kkn1 = *reinterpret_cast<const f32x4*>(qn + 4);
;             wr0 = *reinterpret_cast<const f32x4*>(qn + 2048); wr1 = *reinterpret_cast<const f32x4*>(qn + 2048 + 4);
;             float a0 = reduce8_np(sa0.x + sa0.y), p0 = reduce8_np(yp0.x + yp0.y);
;             float a1 = reduce8_np(sa1.x + sa1.y), p1 = reduce8_np(yp1.x + yp1.y);
;             f32x2 av0 = {a0, a0}, av1 = {a1, a1}, vv0 = {vv.x, vv.x}, vv1 = {vv.y, vv.y};
;             S0[0] += vv0 * kp0.lo; S0[1] += vv0 * kp0.hi; S0[2] += vv0 * kp1.lo; S0[3] += vv0 * kp1.hi;
;             S1[0] += vv1 * kp0.lo; S1[1] += vv1 * kp0.hi; S1[2] += vv1 * kp1.lo; S1[3] += vv1 * kp1.hi;
;             S0[0] += av0 * ka0.lo; S0[1] += av0 * ka0.hi; S0[2] += av0 * ka1.lo; S0[3] += av0 * ka1.hi;
;             S1[0] += av1 * ka0.lo; S1[1] += av1 * ka0.hi; S1[2] += av1 * ka1.lo; S1[3] += av1 * ka1.hi;
;             float y0 = p0 + a0 * cc.x + vv.x * cc.y;
;             float y1 = p1 + a1 * cc.x + vv.y * cc.y;
;             ka0 = *reinterpret_cast<const f32x4*>(qn + 6144); ka1 = *reinterpret_cast<const f32x4*>(qn + 6144 + 4);
;             kp0 = *reinterpret_cast<const f32x4*>(qn + 8192); kp1 = *reinterpret_cast<const f32x4*>(qn + 8192 + 4);
;             vv = *reinterpret_cast<const f32x2*>(B + 10240 + sn * 64 + row0);
;             cc = *reinterpret_cast<const f32x2*>(B + 14336 + sn * 4);
;             yk0 += ym[jj] * y0; yk1 += ym[jj] * y1;
;           }
	ds_read_b128 v[56:59], v200 offset:1792
	ds_read_b128 v[60:63], v200 offset:1808
	ds_read_b128 v[64:67], v200 offset:9984
	ds_read_b128 v[68:71], v200 offset:10000
	ds_read_b128 v[72:75], v200 offset:26368
	ds_read_b128 v[76:79], v200 offset:26384
	ds_read_b128 v[80:83], v200 offset:34560
	ds_read_b128 v[84:87], v200 offset:34576
	ds_read_b64 v[244:245], v201 offset:42752
	ds_read_b64 v[246:247], v202 offset:57456
	v_pk_mul_f32 v[250:251], v[0:1], v[208:209] op_sel_hi:[1,0]
	v_pk_mul_f32 v[252:253], v[0:1], v[216:217] op_sel_hi:[1,0]
	v_pk_fma_f32 v[250:251], v[2:3], v[208:209], v[250:251] op_sel:[0,1,0]
	v_pk_fma_f32 v[252:253], v[2:3], v[216:217], v[252:253] op_sel:[0,1,0]
	v_pk_fma_f32 v[250:251], v[4:5], v[210:211], v[250:251] op_sel_hi:[1,0,1]
	v_pk_fma_f32 v[252:253], v[4:5], v[218:219], v[252:253] op_sel_hi:[1,0,1]
	v_pk_fma_f32 v[250:251], v[6:7], v[210:211], v[250:251] op_sel:[0,1,0]
	v_pk_fma_f32 v[252:253], v[6:7], v[218:219], v[252:253] op_sel:[0,1,0]
	v_pk_fma_f32 v[250:251], v[8:9], v[212:213], v[250:251] op_sel_hi:[1,0,1]
	v_pk_fma_f32 v[252:253], v[8:9], v[220:221], v[252:253] op_sel_hi:[1,0,1]
	v_pk_fma_f32 v[250:251], v[10:11], v[212:213], v[250:251] op_sel:[0,1,0]
	v_pk_fma_f32 v[252:253], v[10:11], v[220:221], v[252:253] op_sel:[0,1,0]
	v_pk_fma_f32 v[250:251], v[12:13], v[214:215], v[250:251] op_sel_hi:[1,0,1]
	v_pk_fma_f32 v[252:253], v[12:13], v[222:223], v[252:253] op_sel_hi:[1,0,1]
	v_pk_fma_f32 v[250:251], v[14:15], v[214:215], v[250:251] op_sel:[0,1,0]
	v_pk_fma_f32 v[252:253], v[14:15], v[222:223], v[252:253] op_sel:[0,1,0]
	v_pk_fma_f32 v[0:1], v[240:241], v[232:233], v[0:1] op_sel_hi:[1,0,1]
	v_add_f32_dpp v250, v250, v250 quad_perm:[1,0,3,2] row_mask:0xf bank_mask:0xf bound_ctrl:1
	v_pk_fma_f32 v[2:3], v[240:241], v[232:233], v[2:3] op_sel:[0,1,0]
	v_add_f32_dpp v251, v251, v251 quad_perm:[1,0,3,2] row_mask:0xf bank_mask:0xf bound_ctrl:1
	v_pk_fma_f32 v[4:5], v[240:241], v[234:235], v[4:5] op_sel_hi:[1,0,1]
	v_add_f32_dpp v250, v250, v250 quad_perm:[2,3,0,1] row_mask:0xf bank_mask:0xf bound_ctrl:1
	v_pk_fma_f32 v[6:7], v[240:241], v[234:235], v[6:7] op_sel:[0,1,0]
	v_add_f32_dpp v251, v251, v251 quad_perm:[2,3,0,1] row_mask:0xf bank_mask:0xf bound_ctrl:1
	v_pk_fma_f32 v[8:9], v[240:241], v[236:237], v[8:9] op_sel_hi:[1,0,1]
	v_add_f32_dpp v250, v250, v250 row_half_mirror row_mask:0xf bank_mask:0xf bound_ctrl:1
	v_pk_fma_f32 v[10:11], v[240:241], v[236:237], v[10:11] op_sel:[0,1,0]
	v_add_f32_dpp v251, v251, v251 row_half_mirror row_mask:0xf bank_mask:0xf bound_ctrl:1
	v_pk_fma_f32 v[12:13], v[240:241], v[238:239], v[12:13] op_sel_hi:[1,0,1]
	v_pk_fma_f32 v[14:15], v[240:241], v[238:239], v[14:15] op_sel:[0,1,0]
	v_pk_fma_f32 v[0:1], v[250:251], v[224:225], v[0:1] op_sel_hi:[1,0,1]
	v_add_f32_dpp v252, v252, v252 quad_perm:[1,0,3,2] row_mask:0xf bank_mask:0xf bound_ctrl:1
	v_pk_fma_f32 v[2:3], v[250:251], v[224:225], v[2:3] op_sel:[0,1,0]
	v_add_f32_dpp v253, v253, v253 quad_perm:[1,0,3,2] row_mask:0xf bank_mask:0xf bound_ctrl:1
	v_pk_fma_f32 v[4:5], v[250:251], v[226:227], v[4:5] op_sel_hi:[1,0,1]
	v_add_f32_dpp v252, v252, v252 quad_perm:[2,3,0,1] row_mask:0xf bank_mask:0xf bound_ctrl:1
	v_pk_fma_f32 v[6:7], v[250:251], v[226:227], v[6:7] op_sel:[0,1,0]
	v_add_f32_dpp v253, v253, v253 quad_perm:[2,3,0,1] row_mask:0xf bank_mask:0xf bound_ctrl:1
	v_pk_fma_f32 v[8:9], v[250:251], v[228:229], v[8:9] op_sel_hi:[1,0,1]
	v_add_f32_dpp v252, v252, v252 row_half_mirror row_mask:0xf bank_mask:0xf bound_ctrl:1
	v_pk_fma_f32 v[10:11], v[250:251], v[228:229], v[10:11] op_sel:[0,1,0]
	v_add_f32_dpp v253, v253, v253 row_half_mirror row_mask:0xf bank_mask:0xf bound_ctrl:1
	v_pk_fma_f32 v[12:13], v[250:251], v[230:231], v[12:13] op_sel_hi:[1,0,1]
	v_pk_fma_f32 v[14:15], v[250:251], v[230:231], v[14:15] op_sel:[0,1,0]
	v_pk_fma_f32 v[248:249], v[250:251], v[242:243], v[252:253] op_sel_hi:[1,0,1]
	v_pk_fma_f32 v[248:249], v[240:241], v[242:243], v[248:249] op_sel:[0,1,0]
	s_mov_b64 exec, s[98:99]
	ds_write_b64 v201, v[248:249] offset:50688
	s_mov_b64 exec, -1
	s_waitcnt lgkmcnt(1)
; __device__ __forceinline__ void phase_scan(const Params& p, int bid, int nblk, int wv) {
;     ...
;           for (int jj = 0; jj < 8; ++jj) {
;             const int s = sb * 8 + jj;
;             const int sn = (s + 1) & 31;
;             const float* qn = q + sn * 64;
;             f32x2 sa0 = S0[0] * kkn0.lo, sa1 = S1[0] * kkn0.lo, yp0 = S0[0] * wr0.lo, yp1 = S1[0] * wr0.lo;
;             sa0 += S0[1] * kkn0.hi; sa1 += S1[1] * kkn0.hi; yp0 += S0[1] * wr0.hi; yp1 += S1[1] * wr0.hi;
;             sa0 += S0[2] * kkn1.lo; sa1 += S1[2] * kkn1.lo; yp0 += S0[2] * wr1.lo; yp1 += S1[2] * wr1.lo;
;             sa0 += S0[3] * kkn1.hi; sa1 += S1[3] * kkn1.hi; yp0 += S0[3] * wr1.hi; yp1 += S1[3] * wr1.hi;
;             kkn0 = *reinterpret_cast<const f32x4*>(qn); kkn1 = *reinterpret_cast<const f32x4*>(qn + 4);
;             wr0 = *reinterpret_cast<const f32x4*>(qn + 2048); wr1 = *reinterpret_cast<const f32x4*>(qn + 2048 + 4);
;             float a0 = reduce8_np(sa0.x + sa0.y), p0 = reduce8_np(yp0.x + yp0.y);
;             float a1 = reduce8_np(sa1.x + sa1.y), p1 = reduce8_np(yp1.x + yp1.y);
;             f32x2 av0 = {a0, a0}, av1 = {a1, a1}, vv0 = {vv.x, vv.x}, vv1 = {vv.y, vv.y};
;             S0[0] += vv0 * kp0.lo; S0[1] += vv0 * kp0.hi; S0[2] += vv0 * kp1.lo; S0[3] += vv0 * kp1.hi;
;             S1[0] += vv1 * kp0.lo; S1[1] += vv1 * kp0.hi; S1[2] += vv1 * kp1.lo; S1[3] += vv1 * kp1.hi;
;             S0[0] += av0 * ka0.lo; S0[1] += av0 * ka0.hi; S0[2] += av0 * ka1.lo; S0[3] += av0 * ka1.hi;
;             S1[0] += av1 * ka0.lo; S1[1] += av1 * ka0.hi; S1[2] += av1 * ka1.lo; S1[3] += av1 * ka1.hi;
;             float y0 = p0 + a0 * cc.x + vv.x * cc.y;
;             float y1 = p1 + a1 * cc.x + vv.y * cc.y;
;             ka0 = *reinterpret_cast<const f32x4*>(qn + 6144); ka1 = *reinterpret_cast<const f32x4*>(qn + 6144 + 4);
;             kp0 = *reinterpret_cast<const f32x4*>(qn + 8192); kp1 = *reinterpret_cast<const f32x4*>(qn + 8192 + 4);
;             vv = *reinterpret_cast<const f32x2*>(B + 10240 + sn * 64 + row0);
;             cc = *reinterpret_cast<const f32x2*>(B + 14336 + sn * 4);
;             yk0 += ym[jj] * y0; yk1 += ym[jj] * y1;
;           }
;           *reinterpret_cast<f32x2*>(B + 12288 + (sb * 8 + kq) * 64 + row0) = f32x2{yk0, yk1};
;           {
	ds_read_b128 v[208:211], v200 offset:2048
	ds_read_b128 v[212:215], v200 offset:2064
	ds_read_b128 v[216:219], v200 offset:10240
	ds_read_b128 v[220:223], v200 offset:10256
	ds_read_b128 v[224:227], v200 offset:26624
	ds_read_b128 v[228:231], v200 offset:26640
	ds_read_b128 v[232:235], v200 offset:34816
	ds_read_b128 v[236:239], v200 offset:34832
	ds_read_b64 v[240:241], v201 offset:43008
	ds_read_b64 v[242:243], v202 offset:57472
	ds_read_b128 v[16:19], v203
	ds_read_b128 v[20:23], v203 offset:16
	v_pk_mul_f32 v[250:251], v[0:1], v[56:57] op_sel_hi:[1,0]
	v_pk_mul_f32 v[252:253], v[0:1], v[64:65] op_sel_hi:[1,0]
	v_pk_fma_f32 v[250:251], v[2:3], v[56:57], v[250:251] op_sel:[0,1,0]
	v_pk_fma_f32 v[252:253], v[2:3], v[64:65], v[252:253] op_sel:[0,1,0]
	v_pk_fma_f32 v[250:251], v[4:5], v[58:59], v[250:251] op_sel_hi:[1,0,1]
	v_pk_fma_f32 v[252:253], v[4:5], v[66:67], v[252:253] op_sel_hi:[1,0,1]
	v_pk_fma_f32 v[250:251], v[6:7], v[58:59], v[250:251] op_sel:[0,1,0]
	v_pk_fma_f32 v[252:253], v[6:7], v[66:67], v[252:253] op_sel:[0,1,0]
	v_pk_fma_f32 v[250:251], v[8:9], v[60:61], v[250:251] op_sel_hi:[1,0,1]
	v_pk_fma_f32 v[252:253], v[8:9], v[68:69], v[252:253] op_sel_hi:[1,0,1]
	v_pk_fma_f32 v[250:251], v[10:11], v[60:61], v[250:251] op_sel:[0,1,0]
	v_pk_fma_f32 v[252:253], v[10:11], v[68:69], v[252:253] op_sel:[0,1,0]
	v_pk_fma_f32 v[250:251], v[12:13], v[62:63], v[250:251] op_sel_hi:[1,0,1]
	v_pk_fma_f32 v[252:253], v[12:13], v[70:71], v[252:253] op_sel_hi:[1,0,1]
	v_pk_fma_f32 v[250:251], v[14:15], v[62:63], v[250:251] op_sel:[0,1,0]
	v_pk_fma_f32 v[252:253], v[14:15], v[70:71], v[252:253] op_sel:[0,1,0]
	v_pk_fma_f32 v[0:1], v[244:245], v[80:81], v[0:1] op_sel_hi:[1,0,1]
	v_add_f32_dpp v250, v250, v250 quad_perm:[1,0,3,2] row_mask:0xf bank_mask:0xf bound_ctrl:1
	v_pk_fma_f32 v[2:3], v[244:245], v[80:81], v[2:3] op_sel:[0,1,0]
	v_add_f32_dpp v251, v251, v251 quad_perm:[1,0,3,2] row_mask:0xf bank_mask:0xf bound_ctrl:1
	v_pk_fma_f32 v[4:5], v[244:245], v[82:83], v[4:5] op_sel_hi:[1,0,1]
	v_add_f32_dpp v250, v250, v250 quad_perm:[2,3,0,1] row_mask:0xf bank_mask:0xf bound_ctrl:1
	v_pk_fma_f32 v[6:7], v[244:245], v[82:83], v[6:7] op_sel:[0,1,0]
	v_add_f32_dpp v251, v251, v251 quad_perm:[2,3,0,1] row_mask:0xf bank_mask:0xf bound_ctrl:1
	v_pk_fma_f32 v[8:9], v[244:245], v[84:85], v[8:9] op_sel_hi:[1,0,1]
	v_add_f32_dpp v250, v250, v250 row_half_mirror row_mask:0xf bank_mask:0xf bound_ctrl:1
	v_pk_fma_f32 v[10:11], v[244:245], v[84:85], v[10:11] op_sel:[0,1,0]
	v_add_f32_dpp v251, v251, v251 row_half_mirror row_mask:0xf bank_mask:0xf bound_ctrl:1
	v_pk_fma_f32 v[12:13], v[244:245], v[86:87], v[12:13] op_sel_hi:[1,0,1]
	v_pk_fma_f32 v[14:15], v[244:245], v[86:87], v[14:15] op_sel:[0,1,0]
	v_pk_fma_f32 v[0:1], v[250:251], v[72:73], v[0:1] op_sel_hi:[1,0,1]
	v_add_f32_dpp v252, v252, v252 quad_perm:[1,0,3,2] row_mask:0xf bank_mask:0xf bound_ctrl:1
	v_pk_fma_f32 v[2:3], v[250:251], v[72:73], v[2:3] op_sel:[0,1,0]
	v_add_f32_dpp v253, v253, v253 quad_perm:[1,0,3,2] row_mask:0xf bank_mask:0xf bound_ctrl:1
	v_pk_fma_f32 v[4:5], v[250:251], v[74:75], v[4:5] op_sel_hi:[1,0,1]
	v_add_f32_dpp v252, v252, v252 quad_perm:[2,3,0,1] row_mask:0xf bank_mask:0xf bound_ctrl:1
	v_pk_fma_f32 v[6:7], v[250:251], v[74:75], v[6:7] op_sel:[0,1,0]
	v_add_f32_dpp v253, v253, v253 quad_perm:[2,3,0,1] row_mask:0xf bank_mask:0xf bound_ctrl:1
	v_pk_fma_f32 v[8:9], v[250:251], v[76:77], v[8:9] op_sel_hi:[1,0,1]
	v_add_f32_dpp v252, v252, v252 row_half_mirror row_mask:0xf bank_mask:0xf bound_ctrl:1
	v_pk_fma_f32 v[10:11], v[250:251], v[76:77], v[10:11] op_sel:[0,1,0]
	v_add_f32_dpp v253, v253, v253 row_half_mirror row_mask:0xf bank_mask:0xf bound_ctrl:1
	v_pk_fma_f32 v[12:13], v[250:251], v[78:79], v[12:13] op_sel_hi:[1,0,1]
	v_pk_fma_f32 v[14:15], v[250:251], v[78:79], v[14:15] op_sel:[0,1,0]
	v_pk_fma_f32 v[248:249], v[250:251], v[246:247], v[252:253] op_sel_hi:[1,0,1]
	v_pk_fma_f32 v[248:249], v[244:245], v[246:247], v[248:249] op_sel:[0,1,0]
	s_mov_b64 exec, s[98:99]
	ds_write_b64 v201, v[248:249] offset:50944
	s_mov_b64 exec, -1
	s_waitcnt lgkmcnt(0)
	v_pk_mul_f32 v[0:1], v[0:1], v[16:17] op_sel_hi:[1,0]
	v_pk_mul_f32 v[2:3], v[2:3], v[16:17] op_sel:[0,1]
	v_pk_mul_f32 v[4:5], v[4:5], v[18:19] op_sel_hi:[1,0]
	v_pk_mul_f32 v[6:7], v[6:7], v[18:19] op_sel:[0,1]
	v_pk_mul_f32 v[8:9], v[8:9], v[20:21] op_sel_hi:[1,0]
	v_pk_mul_f32 v[10:11], v[10:11], v[20:21] op_sel:[0,1]
	v_pk_mul_f32 v[12:13], v[12:13], v[22:23] op_sel_hi:[1,0]
	v_pk_mul_f32 v[14:15], v[14:15], v[22:23] op_sel:[0,1]
	v_add_u32_e32 v200, 0x800, v200
	v_add_u32_e32 v201, 0x800, v201
	v_add_u32_e32 v202, 0x80, v202
	v_add_u32_e32 v203, 0x100, v203
	s_add_i32 s100, s100, -1
	s_cmp_lg_u32 s100, 0
	s_cbranch_scc1 .Lsc_loop
	s_branch .LBB0_931
